# GEMM k-loop DMA groups: M0 write placed before the address add so the add is the required wait state (8 s_nop per k-tile removed in the post-barrier segment)
# speedup vs baseline: 1.0033x; 1.0033x over previous
; #define MFMA(a, b, c) __builtin_amdgcn_mfma_f32_32x32x16_bf16((a), (b), (c), 0, 0, 0)
; #define GEMM_ISSUE(KT, ST) do { const int k1_ = (KT) << 6; unsigned char* d_ = ldst + (ST) * STAGE; \
;         _Pragma("unroll") for (int j_ = 0; j_ < 4; ++j_) dma16(ap + (size_t)(64 * j_) * lda + k1_, d_ + j_ * 8192); \
;         _Pragma("unroll") for (int j_ = 0; j_ < NBW; ++j_) dma16(bp + bro[j_] + k1_, d_ + BOFF + j_ * 8192); } while (0)
; template <int NBW>
; DI void gemm_mainloop(f32x16 (&acc)[2][NBW], const bf16_t* A, size_t lda, int m0, const bf16_t* Bt, size_t ldb, int n0, int K, unsigned char* lds, bool pre = false, bool only_issue = false) {
;     ...
;     for (int kt = 0; kt < nk; ++kt) {
;         const unsigned char* st = lds + (kt & 1) * STAGE;
; #pragma unroll
;         for (int s = 0; s < 4; ++s) {
;             if (s == 1 && kt + 1 < nk) GEMM_ISSUE(kt + 1, (kt + 1) & 1);
;             bf16x8 a[2], b[NBW];
; #pragma unroll
;             for (int mb = 0; mb < 2; ++mb) a[mb] = *(const bf16x8*)(st + aofs + mb * 4096 + xo[s]);
; #pragma unroll
;             for (int nb = 0; nb < NBW; ++nb) b[nb] = *(const bf16x8*)(st + bofs + nb * 4096 + xo[s]);
; #pragma unroll
;             for (int mb = 0; mb < 2; ++mb)
; #pragma unroll
;                 for (int nb = 0; nb < NBW; ++nb) acc[mb][nb] = MFMA(a[mb], b[nb], acc[mb][nb]);
;         }
;         __syncthreads();
;     }
.Lp1_kloop:
	s_waitcnt lgkmcnt(4)
	v_mfma_f32_32x32x16_bf16 v[114:129], v[224:227], v[232:235], v[114:129]
	v_add_u32_e32 v252, v138, v144
	v_add_u32_e32 v253, v149, v144
	ds_read_b128 v[150:153], v252
	s_waitcnt lgkmcnt(4)
	v_mfma_f32_32x32x16_bf16 v[50:65], v[228:231], v[232:235], v[50:65]
	ds_read_b128 v[170:173], v253 offset:32768
	s_waitcnt lgkmcnt(4)
	v_mfma_f32_32x32x16_bf16 v[82:97], v[224:227], v[236:239], v[82:97]
	ds_read_b128 v[166:169], v252 offset:4096
	v_mfma_f32_32x32x16_bf16 v[18:33], v[228:231], v[236:239], v[18:33]
	ds_read_b128 v[174:177], v253 offset:36864
	s_waitcnt lgkmcnt(5)
	v_mfma_f32_32x32x16_bf16 v[98:113], v[224:227], v[240:243], v[98:113]
	ds_read_b128 v[178:181], v253 offset:40960
	v_mfma_f32_32x32x16_bf16 v[34:49], v[228:231], v[240:243], v[34:49]
	ds_read_b128 v[182:185], v253 offset:45056
	s_waitcnt lgkmcnt(6)
	v_mfma_f32_32x32x16_bf16 v[66:81], v[224:227], v[244:247], v[66:81]
	v_mfma_f32_32x32x16_bf16 v[2:17], v[228:231], v[244:247], v[2:17]
	s_waitcnt lgkmcnt(4)
	v_mfma_f32_32x32x16_bf16 v[114:129], v[150:153], v[170:173], v[114:129]
	v_add_u32_e32 v252, v138, v145
	v_add_u32_e32 v253, v149, v145
	ds_read_b128 v[224:227], v252
	s_waitcnt lgkmcnt(4)
	v_mfma_f32_32x32x16_bf16 v[50:65], v[166:169], v[170:173], v[50:65]
	ds_read_b128 v[232:235], v253 offset:32768
	s_waitcnt lgkmcnt(4)
	v_mfma_f32_32x32x16_bf16 v[82:97], v[150:153], v[174:177], v[82:97]
	ds_read_b128 v[228:231], v252 offset:4096
	v_mfma_f32_32x32x16_bf16 v[18:33], v[166:169], v[174:177], v[18:33]
	ds_read_b128 v[236:239], v253 offset:36864
	s_waitcnt lgkmcnt(5)
	v_mfma_f32_32x32x16_bf16 v[98:113], v[150:153], v[178:181], v[98:113]
	ds_read_b128 v[240:243], v253 offset:40960
	v_mfma_f32_32x32x16_bf16 v[34:49], v[166:169], v[178:181], v[34:49]
	ds_read_b128 v[244:247], v253 offset:45056
	s_waitcnt lgkmcnt(6)
	v_mfma_f32_32x32x16_bf16 v[66:81], v[150:153], v[182:185], v[66:81]
	v_mfma_f32_32x32x16_bf16 v[2:17], v[166:169], v[182:185], v[2:17]
	s_waitcnt lgkmcnt(4)
	v_mfma_f32_32x32x16_bf16 v[114:129], v[224:227], v[232:235], v[114:129]
	v_add_u32_e32 v252, v138, v146
	v_add_u32_e32 v253, v149, v146
	ds_read_b128 v[150:153], v252
	s_waitcnt lgkmcnt(4)
	v_mfma_f32_32x32x16_bf16 v[50:65], v[228:231], v[232:235], v[50:65]
	ds_read_b128 v[170:173], v253 offset:32768
	s_waitcnt lgkmcnt(4)
	v_mfma_f32_32x32x16_bf16 v[82:97], v[224:227], v[236:239], v[82:97]
	ds_read_b128 v[166:169], v252 offset:4096
	v_mfma_f32_32x32x16_bf16 v[18:33], v[228:231], v[236:239], v[18:33]
	ds_read_b128 v[174:177], v253 offset:36864
	s_waitcnt lgkmcnt(5)
	v_mfma_f32_32x32x16_bf16 v[98:113], v[224:227], v[240:243], v[98:113]
	ds_read_b128 v[178:181], v253 offset:40960
	v_mfma_f32_32x32x16_bf16 v[34:49], v[228:231], v[240:243], v[34:49]
	ds_read_b128 v[182:185], v253 offset:45056
	s_waitcnt lgkmcnt(6)
	v_mfma_f32_32x32x16_bf16 v[66:81], v[224:227], v[244:247], v[66:81]
	v_mfma_f32_32x32x16_bf16 v[2:17], v[228:231], v[244:247], v[2:17]
	v_xor_b32_e32 v138, 0x10000, v138
	v_xor_b32_e32 v149, 0x10000, v149
	s_waitcnt vmcnt(0) lgkmcnt(0)
	s_barrier
	s_cmp_eq_u32 s2, 0x800
	s_cbranch_scc1 .Lp1_klast
	s_cmp_eq_u32 s2, 0x780
	s_cbranch_scc1 .Lp1_knodma
	v_mfma_f32_32x32x16_bf16 v[114:129], v[150:153], v[170:173], v[114:129]
	v_add_u32_e32 v252, v138, v143
	v_add_u32_e32 v253, v149, v143
	ds_read_b128 v[224:227], v252
	s_and_b32 s19, s18, 0x10000
	v_add_u32_e32 v250, s19, v142
	v_lshl_add_u64 v[248:249], v[130:131], 0, s[2:3]
	s_nop 0
	v_readfirstlane_b32 s19, v250
	s_mov_b64 s[22:23], 0x1080
	s_mov_b32 m0, s19
	v_lshl_add_u64 v[250:251], v[248:249], 0, s[22:23]
	global_load_lds_dwordx4 v[250:251], off
	v_mfma_f32_32x32x16_bf16 v[50:65], v[166:169], v[170:173], v[50:65]
	ds_read_b128 v[232:235], v253 offset:32768
	s_mov_b64 s[22:23], 0x21080
	s_add_i32 m0, s19, 0x2000
	v_lshl_add_u64 v[250:251], v[248:249], 0, s[22:23]
	global_load_lds_dwordx4 v[250:251], off
	v_mfma_f32_32x32x16_bf16 v[82:97], v[150:153], v[174:177], v[82:97]
	ds_read_b128 v[228:231], v252 offset:4096
	s_mov_b64 s[22:23], 0x41080
	s_add_i32 m0, s19, 0x4000
	v_lshl_add_u64 v[250:251], v[248:249], 0, s[22:23]
	global_load_lds_dwordx4 v[250:251], off
	v_mfma_f32_32x32x16_bf16 v[18:33], v[166:169], v[174:177], v[18:33]
	ds_read_b128 v[236:239], v253 offset:36864
	s_mov_b64 s[22:23], 0x61080
	s_add_i32 m0, s19, 0x6000
	v_lshl_add_u64 v[250:251], v[248:249], 0, s[22:23]
	global_load_lds_dwordx4 v[250:251], off
	v_mfma_f32_32x32x16_bf16 v[98:113], v[150:153], v[178:181], v[98:113]
	ds_read_b128 v[240:243], v253 offset:40960
	s_add_i32 m0, s19, 0x8000
	v_lshl_add_u64 v[250:251], v[132:133], 0, s[2:3]
	global_load_lds_dwordx4 v[250:251], off
	v_mfma_f32_32x32x16_bf16 v[34:49], v[166:169], v[178:181], v[34:49]
	ds_read_b128 v[244:247], v253 offset:45056
	s_add_i32 m0, s19, 0xa000
	v_lshl_add_u64 v[250:251], v[134:135], 0, s[2:3]
	global_load_lds_dwordx4 v[250:251], off
	v_mfma_f32_32x32x16_bf16 v[66:81], v[150:153], v[182:185], v[66:81]
	s_add_i32 m0, s19, 0xc000
	v_lshl_add_u64 v[250:251], v[136:137], 0, s[2:3]
	global_load_lds_dwordx4 v[250:251], off
	v_mfma_f32_32x32x16_bf16 v[2:17], v[166:169], v[182:185], v[2:17]
	s_add_i32 m0, s19, 0xe000
	v_lshl_add_u64 v[250:251], v[140:141], 0, s[2:3]
	global_load_lds_dwordx4 v[250:251], off
	s_add_u32 s2, s2, 0x80
	s_addc_u32 s3, s3, 0
	s_add_i32 s18, s18, 0x10000
	s_branch .Lp1_kloop

; #define MFMA(a, b, c) __builtin_amdgcn_mfma_f32_32x32x16_bf16((a), (b), (c), 0, 0, 0)
; #define GEMM_ISSUE(KT, ST) do { const int k1_ = (KT) << 6; unsigned char* d_ = ldst + (ST) * STAGE; \
;         _Pragma("unroll") for (int j_ = 0; j_ < 4; ++j_) dma16(ap + (size_t)(64 * j_) * lda + k1_, d_ + j_ * 8192); \
;         _Pragma("unroll") for (int j_ = 0; j_ < NBW; ++j_) dma16(bp + bro[j_] + k1_, d_ + BOFF + j_ * 8192); } while (0)
; template <int NBW>
; DI void gemm_mainloop(f32x16 (&acc)[2][NBW], const bf16_t* A, size_t lda, int m0, const bf16_t* Bt, size_t ldb, int n0, int K, unsigned char* lds, bool pre = false, bool only_issue = false) {
;     ...
;     for (int kt = 0; kt < nk; ++kt) {
;         const unsigned char* st = lds + (kt & 1) * STAGE;
; #pragma unroll
;         for (int s = 0; s < 4; ++s) {
;             if (s == 1 && kt + 1 < nk) GEMM_ISSUE(kt + 1, (kt + 1) & 1);
;             bf16x8 a[2], b[NBW];
; #pragma unroll
;             for (int mb = 0; mb < 2; ++mb) a[mb] = *(const bf16x8*)(st + aofs + mb * 4096 + xo[s]);
; #pragma unroll
;             for (int nb = 0; nb < NBW; ++nb) b[nb] = *(const bf16x8*)(st + bofs + nb * 4096 + xo[s]);
; #pragma unroll
;             for (int mb = 0; mb < 2; ++mb)
; #pragma unroll
;                 for (int nb = 0; nb < NBW; ++nb) acc[mb][nb] = MFMA(a[mb], b[nb], acc[mb][nb]);
;         }
;         __syncthreads();
;     }
.Lp5_kloop:
	s_waitcnt lgkmcnt(4)
	v_mfma_f32_32x32x16_bf16 v[114:129], v[224:227], v[232:235], v[114:129]
	v_add_u32_e32 v252, v147, v142
	v_add_u32_e32 v253, v148, v142
	ds_read_b128 v[150:153], v252
	s_waitcnt lgkmcnt(4)
	v_mfma_f32_32x32x16_bf16 v[50:65], v[228:231], v[232:235], v[50:65]
	ds_read_b128 v[158:161], v253 offset:32768
	s_waitcnt lgkmcnt(4)
	v_mfma_f32_32x32x16_bf16 v[98:113], v[224:227], v[236:239], v[98:113]
	ds_read_b128 v[154:157], v252 offset:4096
	v_mfma_f32_32x32x16_bf16 v[34:49], v[228:231], v[236:239], v[34:49]
	ds_read_b128 v[170:173], v253 offset:36864
	s_waitcnt lgkmcnt(5)
	v_mfma_f32_32x32x16_bf16 v[82:97], v[224:227], v[240:243], v[82:97]
	ds_read_b128 v[174:177], v253 offset:40960
	v_mfma_f32_32x32x16_bf16 v[18:33], v[228:231], v[240:243], v[18:33]
	ds_read_b128 v[178:181], v253 offset:45056
	s_waitcnt lgkmcnt(6)
	v_mfma_f32_32x32x16_bf16 v[66:81], v[224:227], v[244:247], v[66:81]
	v_mfma_f32_32x32x16_bf16 v[2:17], v[228:231], v[244:247], v[2:17]
	s_waitcnt lgkmcnt(4)
	v_mfma_f32_32x32x16_bf16 v[114:129], v[150:153], v[158:161], v[114:129]
	v_add_u32_e32 v252, v147, v143
	v_add_u32_e32 v253, v148, v143
	ds_read_b128 v[224:227], v252
	s_waitcnt lgkmcnt(4)
	v_mfma_f32_32x32x16_bf16 v[50:65], v[154:157], v[158:161], v[50:65]
	ds_read_b128 v[232:235], v253 offset:32768
	s_waitcnt lgkmcnt(4)
	v_mfma_f32_32x32x16_bf16 v[98:113], v[150:153], v[170:173], v[98:113]
	ds_read_b128 v[228:231], v252 offset:4096
	v_mfma_f32_32x32x16_bf16 v[34:49], v[154:157], v[170:173], v[34:49]
	ds_read_b128 v[236:239], v253 offset:36864
	s_waitcnt lgkmcnt(5)
	v_mfma_f32_32x32x16_bf16 v[82:97], v[150:153], v[174:177], v[82:97]
	ds_read_b128 v[240:243], v253 offset:40960
	v_mfma_f32_32x32x16_bf16 v[18:33], v[154:157], v[174:177], v[18:33]
	ds_read_b128 v[244:247], v253 offset:45056
	s_waitcnt lgkmcnt(6)
	v_mfma_f32_32x32x16_bf16 v[66:81], v[150:153], v[178:181], v[66:81]
	v_mfma_f32_32x32x16_bf16 v[2:17], v[154:157], v[178:181], v[2:17]
	s_waitcnt lgkmcnt(4)
	v_mfma_f32_32x32x16_bf16 v[114:129], v[224:227], v[232:235], v[114:129]
	v_add_u32_e32 v252, v147, v144
	v_add_u32_e32 v253, v148, v144
	ds_read_b128 v[150:153], v252
	s_waitcnt lgkmcnt(4)
	v_mfma_f32_32x32x16_bf16 v[50:65], v[228:231], v[232:235], v[50:65]
	ds_read_b128 v[158:161], v253 offset:32768
	s_waitcnt lgkmcnt(4)
	v_mfma_f32_32x32x16_bf16 v[98:113], v[224:227], v[236:239], v[98:113]
	ds_read_b128 v[154:157], v252 offset:4096
	v_mfma_f32_32x32x16_bf16 v[34:49], v[228:231], v[236:239], v[34:49]
	ds_read_b128 v[170:173], v253 offset:36864
	s_waitcnt lgkmcnt(5)
	v_mfma_f32_32x32x16_bf16 v[82:97], v[224:227], v[240:243], v[82:97]
	ds_read_b128 v[174:177], v253 offset:40960
	v_mfma_f32_32x32x16_bf16 v[18:33], v[228:231], v[240:243], v[18:33]
	ds_read_b128 v[178:181], v253 offset:45056
	s_waitcnt lgkmcnt(6)
	v_mfma_f32_32x32x16_bf16 v[66:81], v[224:227], v[244:247], v[66:81]
	v_mfma_f32_32x32x16_bf16 v[2:17], v[228:231], v[244:247], v[2:17]
	v_xor_b32_e32 v147, 0x10000, v147
	v_xor_b32_e32 v148, 0x10000, v148
	s_waitcnt vmcnt(0) lgkmcnt(0)
	s_barrier
	s_cmp_eq_u32 s22, 0x800
	s_cbranch_scc1 .Lp5_klast
	s_cmp_eq_u32 s22, 0x780
	s_cbranch_scc1 .Lp5_knodma
	v_mfma_f32_32x32x16_bf16 v[114:129], v[150:153], v[158:161], v[114:129]
	v_add_u32_e32 v252, v147, v141
	v_add_u32_e32 v253, v148, v141
	ds_read_b128 v[224:227], v252
	s_and_b32 s29, s27, 0x10000
	v_add_u32_e32 v250, s29, v140
	v_lshl_add_u64 v[248:249], v[130:131], 0, s[22:23]
	s_nop 0
	v_readfirstlane_b32 s29, v250
	s_mov_b32 m0, s29
	v_lshl_add_u64 v[250:251], v[248:249], 0, s[14:15]
	global_load_lds_dwordx4 v[250:251], off
	v_mfma_f32_32x32x16_bf16 v[50:65], v[154:157], v[158:161], v[50:65]
	ds_read_b128 v[232:235], v253 offset:32768
	s_add_i32 m0, s29, 0x2000
	v_lshl_add_u64 v[250:251], v[248:249], 0, s[16:17]
	global_load_lds_dwordx4 v[250:251], off
	v_mfma_f32_32x32x16_bf16 v[98:113], v[150:153], v[170:173], v[98:113]
	ds_read_b128 v[228:231], v252 offset:4096
	s_add_i32 m0, s29, 0x4000
	v_lshl_add_u64 v[250:251], v[248:249], 0, s[18:19]
	global_load_lds_dwordx4 v[250:251], off
	v_mfma_f32_32x32x16_bf16 v[34:49], v[154:157], v[170:173], v[34:49]
	ds_read_b128 v[236:239], v253 offset:36864
	s_add_i32 m0, s29, 0x6000
	v_lshl_add_u64 v[250:251], v[248:249], 0, s[20:21]
	global_load_lds_dwordx4 v[250:251], off
	v_mfma_f32_32x32x16_bf16 v[82:97], v[150:153], v[174:177], v[82:97]
	ds_read_b128 v[240:243], v253 offset:40960
	s_add_i32 m0, s29, 0x8000
	v_lshl_add_u64 v[250:251], v[132:133], 0, s[22:23]
	global_load_lds_dwordx4 v[250:251], off
	v_mfma_f32_32x32x16_bf16 v[18:33], v[154:157], v[174:177], v[18:33]
	ds_read_b128 v[244:247], v253 offset:45056
	s_add_i32 m0, s29, 0xa000
	v_lshl_add_u64 v[250:251], v[134:135], 0, s[22:23]
	global_load_lds_dwordx4 v[250:251], off
	v_mfma_f32_32x32x16_bf16 v[66:81], v[150:153], v[178:181], v[66:81]
	s_add_i32 m0, s29, 0xc000
	v_lshl_add_u64 v[250:251], v[136:137], 0, s[22:23]
	global_load_lds_dwordx4 v[250:251], off
	v_mfma_f32_32x32x16_bf16 v[2:17], v[154:157], v[178:181], v[2:17]
	s_add_i32 m0, s29, 0xe000
	v_lshl_add_u64 v[250:251], v[138:139], 0, s[22:23]
	global_load_lds_dwordx4 v[250:251], off
	s_add_u32 s22, s22, 0x80
	s_addc_u32 s23, s23, 0
	s_add_i32 s27, s27, 0x10000
	s_branch .Lp5_kloop

; #define MFMA(a, b, c) __builtin_amdgcn_mfma_f32_32x32x16_bf16((a), (b), (c), 0, 0, 0)
; #define GEMM_ISSUE(KT, ST) do { const int k1_ = (KT) << 6; unsigned char* d_ = ldst + (ST) * STAGE; \
;         _Pragma("unroll") for (int j_ = 0; j_ < 4; ++j_) dma16(ap + (size_t)(64 * j_) * lda + k1_, d_ + j_ * 8192); \
;         _Pragma("unroll") for (int j_ = 0; j_ < NBW; ++j_) dma16(bp + bro[j_] + k1_, d_ + BOFF + j_ * 8192); } while (0)
; template <int NBW>
; DI void gemm_mainloop(f32x16 (&acc)[2][NBW], const bf16_t* A, size_t lda, int m0, const bf16_t* Bt, size_t ldb, int n0, int K, unsigned char* lds, bool pre = false, bool only_issue = false) {
;     ...
;     for (int kt = 0; kt < nk; ++kt) {
;         const unsigned char* st = lds + (kt & 1) * STAGE;
; #pragma unroll
;         for (int s = 0; s < 4; ++s) {
;             if (s == 1 && kt + 1 < nk) GEMM_ISSUE(kt + 1, (kt + 1) & 1);
;             bf16x8 a[2], b[NBW];
; #pragma unroll
;             for (int mb = 0; mb < 2; ++mb) a[mb] = *(const bf16x8*)(st + aofs + mb * 4096 + xo[s]);
; #pragma unroll
;             for (int nb = 0; nb < NBW; ++nb) b[nb] = *(const bf16x8*)(st + bofs + nb * 4096 + xo[s]);
; #pragma unroll
;             for (int mb = 0; mb < 2; ++mb)
; #pragma unroll
;                 for (int nb = 0; nb < NBW; ++nb) acc[mb][nb] = MFMA(a[mb], b[nb], acc[mb][nb]);
;         }
;         __syncthreads();
;     }
.Lp6_kloop:
	s_waitcnt lgkmcnt(4)
	v_mfma_f32_32x32x16_bf16 v[114:129], v[224:227], v[232:235], v[114:129]
	v_add_u32_e32 v252, v132, v166
	v_add_u32_e32 v253, v171, v166
	ds_read_b128 v[172:175], v252
	s_waitcnt lgkmcnt(4)
	v_mfma_f32_32x32x16_bf16 v[50:65], v[228:231], v[232:235], v[50:65]
	ds_read_b128 v[180:183], v253 offset:32768
	s_waitcnt lgkmcnt(4)
	v_mfma_f32_32x32x16_bf16 v[98:113], v[224:227], v[236:239], v[98:113]
	ds_read_b128 v[176:179], v252 offset:4096
	v_mfma_f32_32x32x16_bf16 v[34:49], v[228:231], v[236:239], v[34:49]
	ds_read_b128 v[184:187], v253 offset:36864
	s_waitcnt lgkmcnt(5)
	v_mfma_f32_32x32x16_bf16 v[82:97], v[224:227], v[240:243], v[82:97]
	ds_read_b128 v[188:191], v253 offset:40960
	v_mfma_f32_32x32x16_bf16 v[18:33], v[228:231], v[240:243], v[18:33]
	ds_read_b128 v[192:195], v253 offset:45056
	s_waitcnt lgkmcnt(6)
	v_mfma_f32_32x32x16_bf16 v[66:81], v[224:227], v[244:247], v[66:81]
	v_mfma_f32_32x32x16_bf16 v[2:17], v[228:231], v[244:247], v[2:17]
	s_waitcnt lgkmcnt(4)
	v_mfma_f32_32x32x16_bf16 v[114:129], v[172:175], v[180:183], v[114:129]
	v_add_u32_e32 v252, v132, v167
	v_add_u32_e32 v253, v171, v167
	ds_read_b128 v[224:227], v252
	s_waitcnt lgkmcnt(4)
	v_mfma_f32_32x32x16_bf16 v[50:65], v[176:179], v[180:183], v[50:65]
	ds_read_b128 v[232:235], v253 offset:32768
	s_waitcnt lgkmcnt(4)
	v_mfma_f32_32x32x16_bf16 v[98:113], v[172:175], v[184:187], v[98:113]
	ds_read_b128 v[228:231], v252 offset:4096
	v_mfma_f32_32x32x16_bf16 v[34:49], v[176:179], v[184:187], v[34:49]
	ds_read_b128 v[236:239], v253 offset:36864
	s_waitcnt lgkmcnt(5)
	v_mfma_f32_32x32x16_bf16 v[82:97], v[172:175], v[188:191], v[82:97]
	ds_read_b128 v[240:243], v253 offset:40960
	v_mfma_f32_32x32x16_bf16 v[18:33], v[176:179], v[188:191], v[18:33]
	ds_read_b128 v[244:247], v253 offset:45056
	s_waitcnt lgkmcnt(6)
	v_mfma_f32_32x32x16_bf16 v[66:81], v[172:175], v[192:195], v[66:81]
	v_mfma_f32_32x32x16_bf16 v[2:17], v[176:179], v[192:195], v[2:17]
	s_waitcnt lgkmcnt(4)
	v_mfma_f32_32x32x16_bf16 v[114:129], v[224:227], v[232:235], v[114:129]
	v_add_u32_e32 v252, v132, v168
	v_add_u32_e32 v253, v171, v168
	ds_read_b128 v[172:175], v252
	s_waitcnt lgkmcnt(4)
	v_mfma_f32_32x32x16_bf16 v[50:65], v[228:231], v[232:235], v[50:65]
	ds_read_b128 v[180:183], v253 offset:32768
	s_waitcnt lgkmcnt(4)
	v_mfma_f32_32x32x16_bf16 v[98:113], v[224:227], v[236:239], v[98:113]
	ds_read_b128 v[176:179], v252 offset:4096
	v_mfma_f32_32x32x16_bf16 v[34:49], v[228:231], v[236:239], v[34:49]
	ds_read_b128 v[184:187], v253 offset:36864
	s_waitcnt lgkmcnt(5)
	v_mfma_f32_32x32x16_bf16 v[82:97], v[224:227], v[240:243], v[82:97]
	ds_read_b128 v[188:191], v253 offset:40960
	v_mfma_f32_32x32x16_bf16 v[18:33], v[228:231], v[240:243], v[18:33]
	ds_read_b128 v[192:195], v253 offset:45056
	s_waitcnt lgkmcnt(6)
	v_mfma_f32_32x32x16_bf16 v[66:81], v[224:227], v[244:247], v[66:81]
	v_mfma_f32_32x32x16_bf16 v[2:17], v[228:231], v[244:247], v[2:17]
	v_xor_b32_e32 v132, 0x10000, v132
	v_xor_b32_e32 v171, 0x10000, v171
	s_waitcnt vmcnt(0) lgkmcnt(0)
	s_barrier
	s_cmp_eq_u32 s28, 0x800
	s_cbranch_scc1 .Lp6_klast
	s_cmp_eq_u32 s28, 0x780
	s_cbranch_scc1 .Lp6_knodma
	v_mfma_f32_32x32x16_bf16 v[114:129], v[172:175], v[180:183], v[114:129]
	v_add_u32_e32 v252, v132, v165
	v_add_u32_e32 v253, v171, v165
	ds_read_b128 v[224:227], v252
	s_and_b32 s30, s27, 0x10000
	v_add_u32_e32 v250, s30, v164
	v_lshl_add_u64 v[248:249], v[134:135], 0, s[28:29]
	s_nop 0
	v_readfirstlane_b32 s30, v250
	s_mov_b32 m0, s30
	v_lshl_add_u64 v[250:251], v[248:249], 0, s[16:17]
	global_load_lds_dwordx4 v[250:251], off
	v_mfma_f32_32x32x16_bf16 v[50:65], v[176:179], v[180:183], v[50:65]
	ds_read_b128 v[232:235], v253 offset:32768
	s_add_i32 m0, s30, 0x2000
	v_lshl_add_u64 v[250:251], v[248:249], 0, s[18:19]
	global_load_lds_dwordx4 v[250:251], off
	v_mfma_f32_32x32x16_bf16 v[98:113], v[172:175], v[184:187], v[98:113]
	ds_read_b128 v[228:231], v252 offset:4096
	s_add_i32 m0, s30, 0x4000
	v_lshl_add_u64 v[250:251], v[248:249], 0, s[20:21]
	global_load_lds_dwordx4 v[250:251], off
	v_mfma_f32_32x32x16_bf16 v[34:49], v[176:179], v[184:187], v[34:49]
	ds_read_b128 v[236:239], v253 offset:36864
	s_add_i32 m0, s30, 0x6000
	v_lshl_add_u64 v[250:251], v[248:249], 0, s[22:23]
	global_load_lds_dwordx4 v[250:251], off
	v_mfma_f32_32x32x16_bf16 v[82:97], v[172:175], v[188:191], v[82:97]
	ds_read_b128 v[240:243], v253 offset:40960
	s_add_i32 m0, s30, 0x8000
	v_lshl_add_u64 v[250:251], v[136:137], 0, s[28:29]
	global_load_lds_dwordx4 v[250:251], off
	v_mfma_f32_32x32x16_bf16 v[18:33], v[176:179], v[188:191], v[18:33]
	ds_read_b128 v[244:247], v253 offset:45056
	s_add_i32 m0, s30, 0xa000
	v_lshl_add_u64 v[250:251], v[138:139], 0, s[28:29]
	global_load_lds_dwordx4 v[250:251], off
	v_mfma_f32_32x32x16_bf16 v[66:81], v[172:175], v[192:195], v[66:81]
	s_add_i32 m0, s30, 0xc000
	v_lshl_add_u64 v[250:251], v[140:141], 0, s[28:29]
	global_load_lds_dwordx4 v[250:251], off
	v_mfma_f32_32x32x16_bf16 v[2:17], v[176:179], v[192:195], v[2:17]
	s_add_i32 m0, s30, 0xe000
	v_lshl_add_u64 v[250:251], v[142:143], 0, s[28:29]
	global_load_lds_dwordx4 v[250:251], off
	s_add_u32 s28, s28, 0x80
	s_addc_u32 s29, s29, 0
	s_add_i32 s27, s27, 0x10000
	s_branch .Lp6_kloop

; #define MFMA(a, b, c) __builtin_amdgcn_mfma_f32_32x32x16_bf16((a), (b), (c), 0, 0, 0)
; #define GEMM_ISSUE(KT, ST) do { const int k1_ = (KT) << 6; unsigned char* d_ = ldst + (ST) * STAGE; \
;         _Pragma("unroll") for (int j_ = 0; j_ < 4; ++j_) dma16(ap + (size_t)(64 * j_) * lda + k1_, d_ + j_ * 8192); \
;         _Pragma("unroll") for (int j_ = 0; j_ < NBW; ++j_) dma16(bp + bro[j_] + k1_, d_ + BOFF + j_ * 8192); } while (0)
; template <int NBW>
; DI void gemm_mainloop(f32x16 (&acc)[2][NBW], const bf16_t* A, size_t lda, int m0, const bf16_t* Bt, size_t ldb, int n0, int K, unsigned char* lds, bool pre = false, bool only_issue = false) {
;     ...
;     for (int kt = 0; kt < nk; ++kt) {
;         const unsigned char* st = lds + (kt & 1) * STAGE;
; #pragma unroll
;         for (int s = 0; s < 4; ++s) {
;             if (s == 1 && kt + 1 < nk) GEMM_ISSUE(kt + 1, (kt + 1) & 1);
;             bf16x8 a[2], b[NBW];
; #pragma unroll
;             for (int mb = 0; mb < 2; ++mb) a[mb] = *(const bf16x8*)(st + aofs + mb * 4096 + xo[s]);
; #pragma unroll
;             for (int nb = 0; nb < NBW; ++nb) b[nb] = *(const bf16x8*)(st + bofs + nb * 4096 + xo[s]);
; #pragma unroll
;             for (int mb = 0; mb < 2; ++mb)
; #pragma unroll
;                 for (int nb = 0; nb < NBW; ++nb) acc[mb][nb] = MFMA(a[mb], b[nb], acc[mb][nb]);
;         }
;         __syncthreads();
;     }
.Lp7_kloop:
	s_waitcnt lgkmcnt(4)
	v_mfma_f32_32x32x16_bf16 v[114:129], v[224:227], v[232:235], v[114:129]
	v_add_u32_e32 v252, v132, v149
	v_add_u32_e32 v253, v154, v149
	ds_read_b128 v[156:159], v252
	s_waitcnt lgkmcnt(4)
	v_mfma_f32_32x32x16_bf16 v[50:65], v[228:231], v[232:235], v[50:65]
	ds_read_b128 v[164:167], v253 offset:32768
	s_waitcnt lgkmcnt(4)
	v_mfma_f32_32x32x16_bf16 v[98:113], v[224:227], v[236:239], v[98:113]
	ds_read_b128 v[160:163], v252 offset:4096
	v_mfma_f32_32x32x16_bf16 v[34:49], v[228:231], v[236:239], v[34:49]
	ds_read_b128 v[168:171], v253 offset:36864
	s_waitcnt lgkmcnt(5)
	v_mfma_f32_32x32x16_bf16 v[82:97], v[224:227], v[240:243], v[82:97]
	ds_read_b128 v[172:175], v253 offset:40960
	v_mfma_f32_32x32x16_bf16 v[18:33], v[228:231], v[240:243], v[18:33]
	ds_read_b128 v[176:179], v253 offset:45056
	s_waitcnt lgkmcnt(6)
	v_mfma_f32_32x32x16_bf16 v[66:81], v[224:227], v[244:247], v[66:81]
	v_mfma_f32_32x32x16_bf16 v[2:17], v[228:231], v[244:247], v[2:17]
	s_waitcnt lgkmcnt(4)
	v_mfma_f32_32x32x16_bf16 v[114:129], v[156:159], v[164:167], v[114:129]
	v_add_u32_e32 v252, v132, v150
	v_add_u32_e32 v253, v154, v150
	ds_read_b128 v[224:227], v252
	s_waitcnt lgkmcnt(4)
	v_mfma_f32_32x32x16_bf16 v[50:65], v[160:163], v[164:167], v[50:65]
	ds_read_b128 v[232:235], v253 offset:32768
	s_waitcnt lgkmcnt(4)
	v_mfma_f32_32x32x16_bf16 v[98:113], v[156:159], v[168:171], v[98:113]
	ds_read_b128 v[228:231], v252 offset:4096
	v_mfma_f32_32x32x16_bf16 v[34:49], v[160:163], v[168:171], v[34:49]
	ds_read_b128 v[236:239], v253 offset:36864
	s_waitcnt lgkmcnt(5)
	v_mfma_f32_32x32x16_bf16 v[82:97], v[156:159], v[172:175], v[82:97]
	ds_read_b128 v[240:243], v253 offset:40960
	v_mfma_f32_32x32x16_bf16 v[18:33], v[160:163], v[172:175], v[18:33]
	ds_read_b128 v[244:247], v253 offset:45056
	s_waitcnt lgkmcnt(6)
	v_mfma_f32_32x32x16_bf16 v[66:81], v[156:159], v[176:179], v[66:81]
	v_mfma_f32_32x32x16_bf16 v[2:17], v[160:163], v[176:179], v[2:17]
	s_waitcnt lgkmcnt(4)
	v_mfma_f32_32x32x16_bf16 v[114:129], v[224:227], v[232:235], v[114:129]
	v_add_u32_e32 v252, v132, v151
	v_add_u32_e32 v253, v154, v151
	ds_read_b128 v[156:159], v252
	s_waitcnt lgkmcnt(4)
	v_mfma_f32_32x32x16_bf16 v[50:65], v[228:231], v[232:235], v[50:65]
	ds_read_b128 v[164:167], v253 offset:32768
	s_waitcnt lgkmcnt(4)
	v_mfma_f32_32x32x16_bf16 v[98:113], v[224:227], v[236:239], v[98:113]
	ds_read_b128 v[160:163], v252 offset:4096
	v_mfma_f32_32x32x16_bf16 v[34:49], v[228:231], v[236:239], v[34:49]
	ds_read_b128 v[168:171], v253 offset:36864
	s_waitcnt lgkmcnt(5)
	v_mfma_f32_32x32x16_bf16 v[82:97], v[224:227], v[240:243], v[82:97]
	ds_read_b128 v[172:175], v253 offset:40960
	v_mfma_f32_32x32x16_bf16 v[18:33], v[228:231], v[240:243], v[18:33]
	ds_read_b128 v[176:179], v253 offset:45056
	s_waitcnt lgkmcnt(6)
	v_mfma_f32_32x32x16_bf16 v[66:81], v[224:227], v[244:247], v[66:81]
	v_mfma_f32_32x32x16_bf16 v[2:17], v[228:231], v[244:247], v[2:17]
	v_xor_b32_e32 v132, 0x10000, v132
	v_xor_b32_e32 v154, 0x10000, v154
	s_waitcnt vmcnt(0) lgkmcnt(0)
	s_barrier
	s_cmp_eq_u32 s22, 0x2000
	s_cbranch_scc1 .Lp7_klast
	s_cmp_eq_u32 s22, 0x1f80
	s_cbranch_scc1 .Lp7_knodma
	v_mfma_f32_32x32x16_bf16 v[114:129], v[156:159], v[164:167], v[114:129]
	v_add_u32_e32 v252, v132, v148
	v_add_u32_e32 v253, v154, v148
	ds_read_b128 v[224:227], v252
	s_and_b32 s24, s21, 0x10000
	v_add_u32_e32 v250, s24, v147
	v_lshl_add_u64 v[248:249], v[134:135], 0, s[22:23]
	s_nop 0
	v_readfirstlane_b32 s24, v250
	s_mov_b32 m0, s24
	v_lshl_add_u64 v[250:251], v[248:249], 0, s[10:11]
	global_load_lds_dwordx4 v[250:251], off
	v_mfma_f32_32x32x16_bf16 v[50:65], v[160:163], v[164:167], v[50:65]
	ds_read_b128 v[232:235], v253 offset:32768
	s_add_i32 m0, s24, 0x2000
	v_lshl_add_u64 v[250:251], v[248:249], 0, s[12:13]
	global_load_lds_dwordx4 v[250:251], off
	v_mfma_f32_32x32x16_bf16 v[98:113], v[156:159], v[168:171], v[98:113]
	ds_read_b128 v[228:231], v252 offset:4096
	s_add_i32 m0, s24, 0x4000
	v_lshl_add_u64 v[250:251], v[248:249], 0, s[14:15]
	global_load_lds_dwordx4 v[250:251], off
	v_mfma_f32_32x32x16_bf16 v[34:49], v[160:163], v[168:171], v[34:49]
	ds_read_b128 v[236:239], v253 offset:36864
	s_add_i32 m0, s24, 0x6000
	v_lshl_add_u64 v[250:251], v[248:249], 0, s[16:17]
	global_load_lds_dwordx4 v[250:251], off
	v_mfma_f32_32x32x16_bf16 v[82:97], v[156:159], v[172:175], v[82:97]
	ds_read_b128 v[240:243], v253 offset:40960
	s_add_i32 m0, s24, 0x8000
	v_lshl_add_u64 v[250:251], v[136:137], 0, s[22:23]
	global_load_lds_dwordx4 v[250:251], off
	v_mfma_f32_32x32x16_bf16 v[18:33], v[160:163], v[172:175], v[18:33]
	ds_read_b128 v[244:247], v253 offset:45056
	s_add_i32 m0, s24, 0xa000
	v_lshl_add_u64 v[250:251], v[138:139], 0, s[22:23]
	global_load_lds_dwordx4 v[250:251], off
	v_mfma_f32_32x32x16_bf16 v[66:81], v[156:159], v[176:179], v[66:81]
	s_add_i32 m0, s24, 0xc000
	v_lshl_add_u64 v[250:251], v[140:141], 0, s[22:23]
	global_load_lds_dwordx4 v[250:251], off
	v_mfma_f32_32x32x16_bf16 v[2:17], v[160:163], v[176:179], v[2:17]
	s_add_i32 m0, s24, 0xe000
	v_lshl_add_u64 v[250:251], v[142:143], 0, s[22:23]
	global_load_lds_dwordx4 v[250:251], off
	s_add_u32 s22, s22, 0x80
	s_addc_u32 s23, s23, 0
	s_add_i32 s21, s21, 0x10000
	s_branch .Lp7_kloop
